# m3 + LN normalise: the 8 (mean,rstd) pairs read once into registers instead of 32 serial LDS reads per call
# baseline (speedup 1.0000x reference)
.LBB0_578:
	v_lshl_add_u32 v188, v200, 3, 0
	s_waitcnt lgkmcnt(0)
	v_cmp_ne_u32_e32 vcc, 0, v162
	ds_read_b64 v[226:227], v188 offset:8192
	ds_read_b64 v[228:229], v188 offset:8320
	ds_read_b64 v[230:231], v188 offset:8448
	ds_read_b64 v[232:233], v188 offset:8576
	ds_read_b64 v[234:235], v188 offset:9216
	ds_read_b64 v[236:237], v188 offset:9344
	ds_read_b64 v[238:239], v188 offset:9472
	ds_read_b64 v[240:241], v188 offset:9600
	s_waitcnt lgkmcnt(0)
	v_mov_b64_e32 v[162:163], v[226:227]
	s_or_b64 s[40:41], vcc, s[58:59]
	v_add_u32_e32 v174, s24, v200
	s_add_u32 s0, s56, 0x3400000
	v_ashrrev_i32_e32 v175, 31, v174
	s_waitcnt lgkmcnt(0)
	v_sub_f32_e32 v69, v69, v162
	v_sub_f32_e32 v68, v68, v162
	v_sub_f32_e32 v67, v67, v162
	v_sub_f32_e32 v66, v66, v162
	s_addc_u32 s1, s57, 0
	v_lshlrev_b64 v[166:167], 10, v[174:175]
	v_pk_mul_f32 v[66:67], v[162:163], v[66:67] op_sel:[1,0]
	v_pk_mul_f32 v[68:69], v[162:163], v[68:69] op_sel:[1,0]
	s_waitcnt vmcnt(0)
	v_pk_fma_f32 v[162:163], v[130:131], v[66:67], v[134:135]
	v_pk_fma_f32 v[164:165], v[132:133], v[68:69], v[136:137]
	s_and_b64 vcc, exec, s[38:39]
	v_lshl_add_u64 v[176:177], v[166:167], 1, s[0:1]
	s_cbranch_vccnz .LBB0_580
	v_pk_fma_f32 v[66:67], v[172:173], v[164:165], v[140:141]
	v_pk_fma_f32 v[68:69], v[170:171], v[162:163], v[138:139]
	s_nop 0
	v_cvt_pk_bf16_f32 v68, v68, v69
	v_cvt_pk_bf16_f32 v66, v66, v67
	s_nop 0
	v_cndmask_b32_e64 v67, v66, v221, s[40:41]
	v_cndmask_b32_e64 v66, v68, v221, s[40:41]
	v_lshl_add_u64 v[68:69], v[160:161], 1, v[176:177]
	global_store_dwordx2 v[68:69], v[66:67], off
.LBB0_580:
	v_mov_b64_e32 v[66:67], v[228:229]
	v_add3_u32 v68, s24, v200, 16
	v_ashrrev_i32_e32 v69, 31, v68
	v_lshlrev_b64 v[68:69], 10, v[68:69]
	s_and_b64 vcc, exec, s[38:39]
	s_waitcnt lgkmcnt(0)
	v_sub_f32_e32 v81, v81, v66
	v_sub_f32_e32 v80, v80, v66
	v_sub_f32_e32 v79, v79, v66
	v_sub_f32_e32 v78, v78, v66
	v_pk_mul_f32 v[78:79], v[66:67], v[78:79] op_sel:[1,0]
	v_pk_mul_f32 v[66:67], v[66:67], v[80:81] op_sel:[1,0]
	v_pk_fma_f32 v[166:167], v[130:131], v[78:79], v[134:135]
	v_pk_fma_f32 v[168:169], v[132:133], v[66:67], v[136:137]
	v_lshl_add_u64 v[182:183], v[68:69], 1, s[0:1]
	s_cbranch_vccnz .LBB0_582
	v_pk_fma_f32 v[66:67], v[172:173], v[168:169], v[140:141]
	v_pk_fma_f32 v[68:69], v[170:171], v[166:167], v[138:139]
	s_nop 0
	v_cvt_pk_bf16_f32 v68, v68, v69
	v_cvt_pk_bf16_f32 v66, v66, v67
	s_nop 0
	v_cndmask_b32_e64 v67, v66, v221, s[40:41]
	v_cndmask_b32_e64 v66, v68, v221, s[40:41]
	v_lshl_add_u64 v[68:69], v[160:161], 1, v[182:183]
	global_store_dwordx2 v[68:69], v[66:67], off
.LBB0_582:
	v_mov_b64_e32 v[66:67], v[230:231]
	v_add3_u32 v68, s24, v200, 32
	v_ashrrev_i32_e32 v69, 31, v68
	v_lshlrev_b64 v[68:69], 10, v[68:69]
	s_and_b64 vcc, exec, s[38:39]
	s_waitcnt lgkmcnt(0)
	v_sub_f32_e32 v79, v109, v66
	v_sub_f32_e32 v78, v108, v66
	v_sub_f32_e32 v81, v107, v66
	v_sub_f32_e32 v80, v106, v66
	v_pk_mul_f32 v[80:81], v[66:67], v[80:81] op_sel:[1,0]
	v_pk_mul_f32 v[66:67], v[66:67], v[78:79] op_sel:[1,0]
	v_pk_fma_f32 v[106:107], v[130:131], v[80:81], v[134:135]
	v_pk_fma_f32 v[108:109], v[132:133], v[66:67], v[136:137]
	v_lshl_add_u64 v[184:185], v[68:69], 1, s[0:1]
	s_cbranch_vccnz .LBB0_584
	v_pk_fma_f32 v[66:67], v[172:173], v[108:109], v[140:141]
	v_pk_fma_f32 v[68:69], v[170:171], v[106:107], v[138:139]
	s_nop 0
	v_cvt_pk_bf16_f32 v68, v68, v69
	v_cvt_pk_bf16_f32 v66, v66, v67
	s_nop 0
	v_cndmask_b32_e64 v67, v66, v221, s[40:41]
	v_cndmask_b32_e64 v66, v68, v221, s[40:41]
	v_lshl_add_u64 v[68:69], v[160:161], 1, v[184:185]
	global_store_dwordx2 v[68:69], v[66:67], off
.LBB0_584:
	v_mov_b64_e32 v[66:67], v[232:233]
	v_add3_u32 v68, s24, v200, 48
	v_ashrrev_i32_e32 v69, 31, v68
	v_lshlrev_b64 v[68:69], 10, v[68:69]
	s_and_b64 vcc, exec, s[38:39]
	s_waitcnt lgkmcnt(0)
	v_sub_f32_e32 v79, v121, v66
	v_sub_f32_e32 v78, v120, v66
	v_sub_f32_e32 v81, v119, v66
	v_sub_f32_e32 v80, v118, v66
	v_pk_mul_f32 v[80:81], v[66:67], v[80:81] op_sel:[1,0]
	v_pk_mul_f32 v[66:67], v[66:67], v[78:79] op_sel:[1,0]
	v_pk_fma_f32 v[118:119], v[130:131], v[80:81], v[134:135]
	v_pk_fma_f32 v[120:121], v[132:133], v[66:67], v[136:137]
	v_lshl_add_u64 v[200:201], v[68:69], 1, s[0:1]
	s_cbranch_vccnz .LBB0_586
	v_pk_fma_f32 v[66:67], v[172:173], v[120:121], v[140:141]
	v_pk_fma_f32 v[68:69], v[170:171], v[118:119], v[138:139]
	s_nop 0
	v_cvt_pk_bf16_f32 v68, v68, v69
	v_cvt_pk_bf16_f32 v66, v66, v67
	s_nop 0
	v_cndmask_b32_e64 v67, v66, v221, s[40:41]
	v_cndmask_b32_e64 v66, v68, v221, s[40:41]
	v_lshl_add_u64 v[68:69], v[160:161], 1, v[200:201]
	global_store_dwordx2 v[68:69], v[66:67], off
.LBB0_586:
	v_mov_b64_e32 v[66:67], v[234:235]
	v_add_u32_e32 v68, 0x80, v174
	v_ashrrev_i32_e32 v69, 31, v68
	v_lshlrev_b64 v[68:69], 10, v[68:69]
	s_and_b64 vcc, exec, s[38:39]
	s_waitcnt lgkmcnt(0)
	v_sub_f32_e32 v79, v129, v66
	v_sub_f32_e32 v78, v128, v66
	v_sub_f32_e32 v81, v127, v66
	v_sub_f32_e32 v80, v126, v66
	v_pk_mul_f32 v[80:81], v[66:67], v[80:81] op_sel:[1,0]
	v_pk_mul_f32 v[66:67], v[66:67], v[78:79] op_sel:[1,0]
	v_pk_fma_f32 v[126:127], v[130:131], v[80:81], v[134:135]
	v_pk_fma_f32 v[128:129], v[132:133], v[66:67], v[136:137]
	v_lshl_add_u64 v[202:203], v[68:69], 1, s[0:1]
	s_cbranch_vccnz .LBB0_588
	v_pk_fma_f32 v[66:67], v[172:173], v[128:129], v[140:141]
	v_pk_fma_f32 v[68:69], v[170:171], v[126:127], v[138:139]
	s_nop 0
	v_cvt_pk_bf16_f32 v68, v68, v69
	v_cvt_pk_bf16_f32 v66, v66, v67
	s_nop 0
	v_cndmask_b32_e64 v67, v66, v221, s[40:41]
	v_cndmask_b32_e64 v66, v68, v221, s[40:41]
	v_lshl_add_u64 v[68:69], v[160:161], 1, v[202:203]
	global_store_dwordx2 v[68:69], v[66:67], off
.LBB0_588:
	v_mov_b64_e32 v[66:67], v[236:237]
	v_add_u32_e32 v68, 0x90, v174
	v_ashrrev_i32_e32 v69, 31, v68
	v_lshlrev_b64 v[68:69], 10, v[68:69]
	s_and_b64 vcc, exec, s[38:39]
	s_waitcnt lgkmcnt(0)
	v_sub_f32_e32 v79, v125, v66
	v_sub_f32_e32 v78, v124, v66
	v_sub_f32_e32 v81, v123, v66
	v_sub_f32_e32 v80, v122, v66
	v_pk_mul_f32 v[80:81], v[66:67], v[80:81] op_sel:[1,0]
	v_pk_mul_f32 v[66:67], v[66:67], v[78:79] op_sel:[1,0]
	v_pk_fma_f32 v[122:123], v[130:131], v[80:81], v[134:135]
	v_pk_fma_f32 v[124:125], v[132:133], v[66:67], v[136:137]
	v_lshl_add_u64 v[204:205], v[68:69], 1, s[0:1]
	s_cbranch_vccnz .LBB0_590
	v_pk_fma_f32 v[66:67], v[172:173], v[124:125], v[140:141]
	v_pk_fma_f32 v[68:69], v[170:171], v[122:123], v[138:139]
	s_nop 0
	v_cvt_pk_bf16_f32 v68, v68, v69
	v_cvt_pk_bf16_f32 v66, v66, v67
	s_nop 0
	v_cndmask_b32_e64 v67, v66, v221, s[40:41]
	v_cndmask_b32_e64 v66, v68, v221, s[40:41]
	v_lshl_add_u64 v[68:69], v[160:161], 1, v[204:205]
	global_store_dwordx2 v[68:69], v[66:67], off
.LBB0_590:
	v_mov_b64_e32 v[66:67], v[238:239]
	v_add_u32_e32 v68, 0xa0, v174
	v_ashrrev_i32_e32 v69, 31, v68
	v_lshlrev_b64 v[68:69], 10, v[68:69]
	s_and_b64 vcc, exec, s[38:39]
	s_waitcnt lgkmcnt(0)
	v_sub_f32_e32 v79, v113, v66
	v_sub_f32_e32 v78, v112, v66
	v_sub_f32_e32 v81, v111, v66
	v_sub_f32_e32 v80, v110, v66
	v_pk_mul_f32 v[80:81], v[66:67], v[80:81] op_sel:[1,0]
	v_pk_mul_f32 v[66:67], v[66:67], v[78:79] op_sel:[1,0]
	v_pk_fma_f32 v[110:111], v[130:131], v[80:81], v[134:135]
	v_pk_fma_f32 v[112:113], v[132:133], v[66:67], v[136:137]
	v_lshl_add_u64 v[206:207], v[68:69], 1, s[0:1]
	s_cbranch_vccnz .LBB0_592
	v_pk_fma_f32 v[66:67], v[172:173], v[112:113], v[140:141]
	v_pk_fma_f32 v[68:69], v[170:171], v[110:111], v[138:139]
	s_nop 0
	v_cvt_pk_bf16_f32 v68, v68, v69
	v_cvt_pk_bf16_f32 v66, v66, v67
	s_nop 0
	v_cndmask_b32_e64 v67, v66, v221, s[40:41]
	v_cndmask_b32_e64 v66, v68, v221, s[40:41]
	v_lshl_add_u64 v[68:69], v[160:161], 1, v[206:207]
	global_store_dwordx2 v[68:69], v[66:67], off
.LBB0_592:
	v_mov_b64_e32 v[66:67], v[240:241]
	v_add_u32_e32 v68, 0xb0, v174
	v_ashrrev_i32_e32 v69, 31, v68
	v_lshlrev_b64 v[68:69], 10, v[68:69]
	s_and_b64 vcc, exec, s[38:39]
	s_waitcnt lgkmcnt(0)
	v_sub_f32_e32 v79, v97, v66
	v_sub_f32_e32 v78, v96, v66
	v_sub_f32_e32 v81, v95, v66
	v_sub_f32_e32 v80, v94, v66
	v_pk_mul_f32 v[80:81], v[66:67], v[80:81] op_sel:[1,0]
	v_pk_mul_f32 v[66:67], v[66:67], v[78:79] op_sel:[1,0]
	v_pk_fma_f32 v[130:131], v[130:131], v[80:81], v[134:135]
	v_pk_fma_f32 v[132:133], v[132:133], v[66:67], v[136:137]
	v_lshl_add_u64 v[208:209], v[68:69], 1, s[0:1]
	s_cbranch_vccnz .LBB0_594
	v_pk_fma_f32 v[66:67], v[172:173], v[132:133], v[140:141]
	v_pk_fma_f32 v[68:69], v[170:171], v[130:131], v[138:139]
	s_nop 0
	v_cvt_pk_bf16_f32 v68, v68, v69
	v_cvt_pk_bf16_f32 v66, v66, v67
	s_nop 0
	v_cndmask_b32_e64 v67, v66, v221, s[40:41]
	v_cndmask_b32_e64 v66, v68, v221, s[40:41]
	v_lshl_add_u64 v[68:69], v[160:161], 1, v[208:209]
	global_store_dwordx2 v[68:69], v[66:67], off

.LBB0_596:
	v_mov_b64_e32 v[134:135], v[226:227]
	s_and_b64 vcc, exec, s[38:39]
	s_waitcnt lgkmcnt(0)
	v_sub_f32_e32 v37, v37, v134
	v_sub_f32_e32 v36, v36, v134
	v_sub_f32_e32 v35, v35, v134
	v_sub_f32_e32 v34, v34, v134
	v_pk_mul_f32 v[34:35], v[134:135], v[34:35] op_sel:[1,0]
	v_pk_mul_f32 v[36:37], v[134:135], v[36:37] op_sel:[1,0]
	s_waitcnt vmcnt(0)
	v_pk_fma_f32 v[138:139], v[66:67], v[34:35], v[78:79]
	v_pk_fma_f32 v[134:135], v[68:69], v[36:37], v[80:81]
	s_cbranch_vccnz .LBB0_598
	v_pk_fma_f32 v[34:35], v[212:213], v[134:135], v[96:97]
	v_pk_fma_f32 v[36:37], v[210:211], v[138:139], v[94:95]
	s_nop 0
	v_cvt_pk_bf16_f32 v36, v36, v37
	v_cvt_pk_bf16_f32 v34, v34, v35
	s_nop 0
	v_cndmask_b32_e64 v35, v34, v221, s[40:41]
	v_cndmask_b32_e64 v34, v36, v221, s[40:41]
	v_lshl_add_u64 v[36:37], v[160:161], 1, v[176:177]
	global_store_dwordx2 v[36:37], v[34:35], off offset:32
.LBB0_598:
	v_mov_b64_e32 v[34:35], v[228:229]
	s_and_b64 vcc, exec, s[38:39]
	s_waitcnt lgkmcnt(0)
	v_sub_f32_e32 v37, v49, v34
	v_sub_f32_e32 v36, v48, v34
	v_sub_f32_e32 v47, v47, v34
	v_sub_f32_e32 v46, v46, v34
	v_pk_mul_f32 v[46:47], v[34:35], v[46:47] op_sel:[1,0]
	v_pk_mul_f32 v[34:35], v[34:35], v[36:37] op_sel:[1,0]
	v_pk_fma_f32 v[140:141], v[66:67], v[46:47], v[78:79]
	v_pk_fma_f32 v[136:137], v[68:69], v[34:35], v[80:81]
	s_cbranch_vccnz .LBB0_600
	v_pk_fma_f32 v[34:35], v[212:213], v[136:137], v[96:97]
	v_pk_fma_f32 v[36:37], v[210:211], v[140:141], v[94:95]
	s_nop 0
	v_cvt_pk_bf16_f32 v36, v36, v37
	v_cvt_pk_bf16_f32 v34, v34, v35
	s_nop 0
	v_cndmask_b32_e64 v35, v34, v221, s[40:41]
	v_cndmask_b32_e64 v34, v36, v221, s[40:41]
	v_lshl_add_u64 v[36:37], v[160:161], 1, v[182:183]
	global_store_dwordx2 v[36:37], v[34:35], off offset:32
.LBB0_600:
	v_mov_b64_e32 v[34:35], v[230:231]
	s_and_b64 vcc, exec, s[38:39]
	s_waitcnt lgkmcnt(0)
	v_sub_f32_e32 v37, v65, v34
	v_sub_f32_e32 v36, v64, v34
	v_sub_f32_e32 v47, v63, v34
	v_sub_f32_e32 v46, v62, v34
	v_pk_mul_f32 v[46:47], v[34:35], v[46:47] op_sel:[1,0]
	v_pk_mul_f32 v[34:35], v[34:35], v[36:37] op_sel:[1,0]
	v_pk_fma_f32 v[172:173], v[66:67], v[46:47], v[78:79]
	v_pk_fma_f32 v[170:171], v[68:69], v[34:35], v[80:81]
	s_cbranch_vccnz .LBB0_602
	v_pk_fma_f32 v[34:35], v[212:213], v[170:171], v[96:97]
	v_pk_fma_f32 v[36:37], v[210:211], v[172:173], v[94:95]
	s_nop 0
	v_cvt_pk_bf16_f32 v36, v36, v37
	v_cvt_pk_bf16_f32 v34, v34, v35
	s_nop 0
	v_cndmask_b32_e64 v35, v34, v221, s[40:41]
	v_cndmask_b32_e64 v34, v36, v221, s[40:41]
	v_lshl_add_u64 v[36:37], v[160:161], 1, v[184:185]
	global_store_dwordx2 v[36:37], v[34:35], off offset:32
.LBB0_602:
	v_mov_b64_e32 v[34:35], v[232:233]
	s_and_b64 vcc, exec, s[38:39]
	s_waitcnt lgkmcnt(0)
	v_sub_f32_e32 v37, v77, v34
	v_sub_f32_e32 v36, v76, v34
	v_sub_f32_e32 v47, v75, v34
	v_sub_f32_e32 v46, v74, v34
	v_pk_mul_f32 v[46:47], v[34:35], v[46:47] op_sel:[1,0]
	v_pk_mul_f32 v[34:35], v[34:35], v[36:37] op_sel:[1,0]
	v_pk_fma_f32 v[76:77], v[66:67], v[46:47], v[78:79]
	v_pk_fma_f32 v[74:75], v[68:69], v[34:35], v[80:81]
	s_cbranch_vccnz .LBB0_604
	v_pk_fma_f32 v[34:35], v[212:213], v[74:75], v[96:97]
	v_pk_fma_f32 v[36:37], v[210:211], v[76:77], v[94:95]
	s_nop 0
	v_cvt_pk_bf16_f32 v36, v36, v37
	v_cvt_pk_bf16_f32 v34, v34, v35
	s_nop 0
	v_cndmask_b32_e64 v35, v34, v221, s[40:41]
	v_cndmask_b32_e64 v34, v36, v221, s[40:41]
	v_lshl_add_u64 v[36:37], v[160:161], 1, v[200:201]
	global_store_dwordx2 v[36:37], v[34:35], off offset:32
.LBB0_604:
	v_mov_b64_e32 v[34:35], v[234:235]
	s_and_b64 vcc, exec, s[38:39]
	s_waitcnt lgkmcnt(0)
	v_sub_f32_e32 v37, v101, v34
	v_sub_f32_e32 v36, v100, v34
	v_sub_f32_e32 v47, v99, v34
	v_sub_f32_e32 v46, v98, v34
	v_pk_mul_f32 v[46:47], v[34:35], v[46:47] op_sel:[1,0]
	v_pk_mul_f32 v[34:35], v[34:35], v[36:37] op_sel:[1,0]
	v_pk_fma_f32 v[174:175], v[66:67], v[46:47], v[78:79]
	v_pk_fma_f32 v[98:99], v[68:69], v[34:35], v[80:81]
	s_cbranch_vccnz .LBB0_606
	v_pk_fma_f32 v[34:35], v[212:213], v[98:99], v[96:97]
	v_pk_fma_f32 v[36:37], v[210:211], v[174:175], v[94:95]
	s_nop 0
	v_cvt_pk_bf16_f32 v36, v36, v37
	v_cvt_pk_bf16_f32 v34, v34, v35
	s_nop 0
	v_cndmask_b32_e64 v35, v34, v221, s[40:41]
	v_cndmask_b32_e64 v34, v36, v221, s[40:41]
	v_lshl_add_u64 v[36:37], v[160:161], 1, v[202:203]
	global_store_dwordx2 v[36:37], v[34:35], off offset:32
.LBB0_606:
	v_mov_b64_e32 v[34:35], v[236:237]
	s_and_b64 vcc, exec, s[38:39]
	s_waitcnt lgkmcnt(0)
	v_sub_f32_e32 v37, v117, v34
	v_sub_f32_e32 v36, v116, v34
	v_sub_f32_e32 v47, v115, v34
	v_sub_f32_e32 v46, v114, v34
	v_pk_mul_f32 v[46:47], v[34:35], v[46:47] op_sel:[1,0]
	v_pk_mul_f32 v[34:35], v[34:35], v[36:37] op_sel:[1,0]
	v_pk_fma_f32 v[114:115], v[66:67], v[46:47], v[78:79]
	v_pk_fma_f32 v[100:101], v[68:69], v[34:35], v[80:81]
	s_cbranch_vccnz .LBB0_608
	v_pk_fma_f32 v[34:35], v[212:213], v[100:101], v[96:97]
	v_pk_fma_f32 v[36:37], v[210:211], v[114:115], v[94:95]
	s_nop 0
	v_cvt_pk_bf16_f32 v36, v36, v37
	v_cvt_pk_bf16_f32 v34, v34, v35
	s_nop 0
	v_cndmask_b32_e64 v35, v34, v221, s[40:41]
	v_cndmask_b32_e64 v34, v36, v221, s[40:41]
	v_lshl_add_u64 v[36:37], v[160:161], 1, v[204:205]
	global_store_dwordx2 v[36:37], v[34:35], off offset:32
.LBB0_608:
	v_mov_b64_e32 v[34:35], v[238:239]
	s_and_b64 vcc, exec, s[38:39]
	s_waitcnt lgkmcnt(0)
	v_sub_f32_e32 v37, v105, v34
	v_sub_f32_e32 v36, v104, v34
	v_sub_f32_e32 v47, v103, v34
	v_sub_f32_e32 v46, v102, v34
	v_pk_mul_f32 v[46:47], v[34:35], v[46:47] op_sel:[1,0]
	v_pk_mul_f32 v[34:35], v[34:35], v[36:37] op_sel:[1,0]
	v_pk_fma_f32 v[104:105], v[66:67], v[46:47], v[78:79]
	v_pk_fma_f32 v[102:103], v[68:69], v[34:35], v[80:81]
	s_cbranch_vccnz .LBB0_610
	v_pk_fma_f32 v[34:35], v[212:213], v[102:103], v[96:97]
	v_pk_fma_f32 v[36:37], v[210:211], v[104:105], v[94:95]
	s_nop 0
	v_cvt_pk_bf16_f32 v36, v36, v37
	v_cvt_pk_bf16_f32 v34, v34, v35
	s_nop 0
	v_cndmask_b32_e64 v35, v34, v221, s[40:41]
	v_cndmask_b32_e64 v34, v36, v221, s[40:41]
	v_lshl_add_u64 v[36:37], v[160:161], 1, v[206:207]
	global_store_dwordx2 v[36:37], v[34:35], off offset:32
.LBB0_610:
	v_mov_b64_e32 v[34:35], v[240:241]
	s_and_b64 vcc, exec, s[38:39]
	s_waitcnt lgkmcnt(0)
	v_sub_f32_e32 v37, v93, v34
	v_sub_f32_e32 v36, v92, v34
	v_sub_f32_e32 v47, v91, v34
	v_sub_f32_e32 v46, v90, v34
	v_pk_mul_f32 v[46:47], v[34:35], v[46:47] op_sel:[1,0]
	v_pk_mul_f32 v[34:35], v[34:35], v[36:37] op_sel:[1,0]
	v_pk_fma_f32 v[66:67], v[66:67], v[46:47], v[78:79]
	v_pk_fma_f32 v[68:69], v[68:69], v[34:35], v[80:81]
	s_cbranch_vccnz .LBB0_612
	v_pk_fma_f32 v[34:35], v[212:213], v[68:69], v[96:97]
	v_pk_fma_f32 v[36:37], v[210:211], v[66:67], v[94:95]
	s_nop 0
	v_cvt_pk_bf16_f32 v36, v36, v37
	v_cvt_pk_bf16_f32 v34, v34, v35
	s_nop 0
	v_cndmask_b32_e64 v35, v34, v221, s[40:41]
	v_cndmask_b32_e64 v34, v36, v221, s[40:41]
	v_lshl_add_u64 v[36:37], v[160:161], 1, v[208:209]
	global_store_dwordx2 v[36:37], v[34:35], off offset:32

.LBB0_614:
	v_mov_b64_e32 v[78:79], v[226:227]
	s_and_b64 vcc, exec, s[38:39]
	s_waitcnt lgkmcnt(0)
	v_sub_f32_e32 v17, v17, v78
	v_sub_f32_e32 v16, v16, v78
	v_sub_f32_e32 v15, v15, v78
	v_sub_f32_e32 v14, v14, v78
	v_pk_mul_f32 v[14:15], v[78:79], v[14:15] op_sel:[1,0]
	v_pk_mul_f32 v[16:17], v[78:79], v[16:17] op_sel:[1,0]
	s_waitcnt vmcnt(0)
	v_pk_fma_f32 v[90:91], v[34:35], v[14:15], v[46:47]
	v_pk_fma_f32 v[78:79], v[36:37], v[16:17], v[48:49]
	s_cbranch_vccnz .LBB0_616
	v_pk_fma_f32 v[14:15], v[212:213], v[78:79], v[64:65]
	v_pk_fma_f32 v[16:17], v[210:211], v[90:91], v[62:63]
	s_nop 0
	v_cvt_pk_bf16_f32 v16, v16, v17
	v_cvt_pk_bf16_f32 v14, v14, v15
	s_nop 0
	v_cndmask_b32_e64 v15, v14, v221, s[40:41]
	v_cndmask_b32_e64 v14, v16, v221, s[40:41]
	v_lshl_add_u64 v[16:17], v[160:161], 1, v[176:177]
	global_store_dwordx2 v[16:17], v[14:15], off offset:256
.LBB0_616:
	v_mov_b64_e32 v[14:15], v[228:229]
	s_and_b64 vcc, exec, s[38:39]
	s_waitcnt lgkmcnt(0)
	v_sub_f32_e32 v17, v25, v14
	v_sub_f32_e32 v16, v24, v14
	v_sub_f32_e32 v23, v23, v14
	v_sub_f32_e32 v22, v22, v14
	v_pk_mul_f32 v[22:23], v[14:15], v[22:23] op_sel:[1,0]
	v_pk_mul_f32 v[14:15], v[14:15], v[16:17] op_sel:[1,0]
	v_pk_fma_f32 v[92:93], v[34:35], v[22:23], v[46:47]
	v_pk_fma_f32 v[80:81], v[36:37], v[14:15], v[48:49]
	s_cbranch_vccnz .LBB0_618
	v_pk_fma_f32 v[14:15], v[212:213], v[80:81], v[64:65]
	v_pk_fma_f32 v[16:17], v[210:211], v[92:93], v[62:63]
	s_nop 0
	v_cvt_pk_bf16_f32 v16, v16, v17
	v_cvt_pk_bf16_f32 v14, v14, v15
	s_nop 0
	v_cndmask_b32_e64 v15, v14, v221, s[40:41]
	v_cndmask_b32_e64 v14, v16, v221, s[40:41]
	v_lshl_add_u64 v[16:17], v[160:161], 1, v[182:183]
	global_store_dwordx2 v[16:17], v[14:15], off offset:256
.LBB0_618:
	v_mov_b64_e32 v[14:15], v[230:231]
	s_and_b64 vcc, exec, s[38:39]
	s_waitcnt lgkmcnt(0)
	v_sub_f32_e32 v17, v33, v14
	v_sub_f32_e32 v16, v32, v14
	v_sub_f32_e32 v23, v31, v14
	v_sub_f32_e32 v22, v30, v14
	v_pk_mul_f32 v[22:23], v[14:15], v[22:23] op_sel:[1,0]
	v_pk_mul_f32 v[14:15], v[14:15], v[16:17] op_sel:[1,0]
	v_pk_fma_f32 v[96:97], v[34:35], v[22:23], v[46:47]
	v_pk_fma_f32 v[94:95], v[36:37], v[14:15], v[48:49]
	s_cbranch_vccnz .LBB0_620
	v_pk_fma_f32 v[14:15], v[212:213], v[94:95], v[64:65]
	v_pk_fma_f32 v[16:17], v[210:211], v[96:97], v[62:63]
	s_nop 0
	v_cvt_pk_bf16_f32 v16, v16, v17
	v_cvt_pk_bf16_f32 v14, v14, v15
	s_nop 0
	v_cndmask_b32_e64 v15, v14, v221, s[40:41]
	v_cndmask_b32_e64 v14, v16, v221, s[40:41]
	v_lshl_add_u64 v[16:17], v[160:161], 1, v[184:185]
	global_store_dwordx2 v[16:17], v[14:15], off offset:256
.LBB0_620:
	v_mov_b64_e32 v[14:15], v[232:233]
	s_and_b64 vcc, exec, s[38:39]
	s_waitcnt lgkmcnt(0)
	v_sub_f32_e32 v17, v45, v14
	v_sub_f32_e32 v16, v44, v14
	v_sub_f32_e32 v23, v43, v14
	v_sub_f32_e32 v22, v42, v14
	v_pk_mul_f32 v[22:23], v[14:15], v[22:23] op_sel:[1,0]
	v_pk_mul_f32 v[14:15], v[14:15], v[16:17] op_sel:[1,0]
	v_pk_fma_f32 v[44:45], v[34:35], v[22:23], v[46:47]
	v_pk_fma_f32 v[42:43], v[36:37], v[14:15], v[48:49]
	s_cbranch_vccnz .LBB0_622
	v_pk_fma_f32 v[14:15], v[212:213], v[42:43], v[64:65]
	v_pk_fma_f32 v[16:17], v[210:211], v[44:45], v[62:63]
	s_nop 0
	v_cvt_pk_bf16_f32 v16, v16, v17
	v_cvt_pk_bf16_f32 v14, v14, v15
	s_nop 0
	v_cndmask_b32_e64 v15, v14, v221, s[40:41]
	v_cndmask_b32_e64 v14, v16, v221, s[40:41]
	v_lshl_add_u64 v[16:17], v[160:161], 1, v[200:201]
	global_store_dwordx2 v[16:17], v[14:15], off offset:256
.LBB0_622:
	v_mov_b64_e32 v[14:15], v[234:235]
	s_and_b64 vcc, exec, s[38:39]
	s_waitcnt lgkmcnt(0)
	v_sub_f32_e32 v17, v61, v14
	v_sub_f32_e32 v16, v60, v14
	v_sub_f32_e32 v23, v59, v14
	v_sub_f32_e32 v22, v58, v14
	v_pk_mul_f32 v[22:23], v[14:15], v[22:23] op_sel:[1,0]
	v_pk_mul_f32 v[14:15], v[14:15], v[16:17] op_sel:[1,0]
	v_pk_fma_f32 v[116:117], v[34:35], v[22:23], v[46:47]
	v_pk_fma_f32 v[58:59], v[36:37], v[14:15], v[48:49]
	s_cbranch_vccnz .LBB0_624
	v_pk_fma_f32 v[14:15], v[212:213], v[58:59], v[64:65]
	v_pk_fma_f32 v[16:17], v[210:211], v[116:117], v[62:63]
	s_nop 0
	v_cvt_pk_bf16_f32 v16, v16, v17
	v_cvt_pk_bf16_f32 v14, v14, v15
	s_nop 0
	v_cndmask_b32_e64 v15, v14, v221, s[40:41]
	v_cndmask_b32_e64 v14, v16, v221, s[40:41]
	v_lshl_add_u64 v[16:17], v[160:161], 1, v[202:203]
	global_store_dwordx2 v[16:17], v[14:15], off offset:256
.LBB0_624:
	v_mov_b64_e32 v[14:15], v[236:237]
	s_and_b64 vcc, exec, s[38:39]
	s_waitcnt lgkmcnt(0)
	v_sub_f32_e32 v17, v73, v14
	v_sub_f32_e32 v16, v72, v14
	v_sub_f32_e32 v23, v71, v14
	v_sub_f32_e32 v22, v70, v14
	v_pk_mul_f32 v[22:23], v[14:15], v[22:23] op_sel:[1,0]
	v_pk_mul_f32 v[14:15], v[14:15], v[16:17] op_sel:[1,0]
	v_pk_fma_f32 v[70:71], v[34:35], v[22:23], v[46:47]
	v_pk_fma_f32 v[60:61], v[36:37], v[14:15], v[48:49]
	s_cbranch_vccnz .LBB0_626
	v_pk_fma_f32 v[14:15], v[212:213], v[60:61], v[64:65]
	v_pk_fma_f32 v[16:17], v[210:211], v[70:71], v[62:63]
	s_nop 0
	v_cvt_pk_bf16_f32 v16, v16, v17
	v_cvt_pk_bf16_f32 v14, v14, v15
	s_nop 0
	v_cndmask_b32_e64 v15, v14, v221, s[40:41]
	v_cndmask_b32_e64 v14, v16, v221, s[40:41]
	v_lshl_add_u64 v[16:17], v[160:161], 1, v[204:205]
	global_store_dwordx2 v[16:17], v[14:15], off offset:256
.LBB0_626:
	v_mov_b64_e32 v[14:15], v[238:239]
	s_and_b64 vcc, exec, s[38:39]
	s_waitcnt lgkmcnt(0)
	v_sub_f32_e32 v17, v89, v14
	v_sub_f32_e32 v16, v88, v14
	v_sub_f32_e32 v23, v87, v14
	v_sub_f32_e32 v22, v86, v14
	v_pk_mul_f32 v[22:23], v[14:15], v[22:23] op_sel:[1,0]
	v_pk_mul_f32 v[14:15], v[14:15], v[16:17] op_sel:[1,0]
	v_pk_fma_f32 v[86:87], v[34:35], v[22:23], v[46:47]
	v_pk_fma_f32 v[72:73], v[36:37], v[14:15], v[48:49]
	s_cbranch_vccnz .LBB0_628
	v_pk_fma_f32 v[14:15], v[212:213], v[72:73], v[64:65]
	v_pk_fma_f32 v[16:17], v[210:211], v[86:87], v[62:63]
	s_nop 0
	v_cvt_pk_bf16_f32 v16, v16, v17
	v_cvt_pk_bf16_f32 v14, v14, v15
	s_nop 0
	v_cndmask_b32_e64 v15, v14, v221, s[40:41]
	v_cndmask_b32_e64 v14, v16, v221, s[40:41]
	v_lshl_add_u64 v[16:17], v[160:161], 1, v[206:207]
	global_store_dwordx2 v[16:17], v[14:15], off offset:256
.LBB0_628:
	v_mov_b64_e32 v[14:15], v[240:241]
	s_and_b64 vcc, exec, s[38:39]
	s_waitcnt lgkmcnt(0)
	v_sub_f32_e32 v17, v85, v14
	v_sub_f32_e32 v16, v84, v14
	v_sub_f32_e32 v23, v83, v14
	v_sub_f32_e32 v22, v82, v14
	v_pk_mul_f32 v[22:23], v[14:15], v[22:23] op_sel:[1,0]
	v_pk_mul_f32 v[14:15], v[14:15], v[16:17] op_sel:[1,0]
	v_pk_fma_f32 v[34:35], v[34:35], v[22:23], v[46:47]
	v_pk_fma_f32 v[36:37], v[36:37], v[14:15], v[48:49]
	s_cbranch_vccnz .LBB0_630
	v_pk_fma_f32 v[14:15], v[212:213], v[36:37], v[64:65]
	v_pk_fma_f32 v[16:17], v[210:211], v[34:35], v[62:63]
	s_nop 0
	v_cvt_pk_bf16_f32 v16, v16, v17
	v_cvt_pk_bf16_f32 v14, v14, v15
	s_nop 0
	v_cndmask_b32_e64 v15, v14, v221, s[40:41]
	v_cndmask_b32_e64 v14, v16, v221, s[40:41]
	v_lshl_add_u64 v[16:17], v[160:161], 1, v[208:209]
	global_store_dwordx2 v[16:17], v[14:15], off offset:256

.LBB0_632:
	v_mov_b64_e32 v[46:47], v[226:227]
	s_and_b64 vcc, exec, s[38:39]
	s_waitcnt lgkmcnt(0)
	v_sub_f32_e32 v5, v5, v46
	v_sub_f32_e32 v4, v4, v46
	v_sub_f32_e32 v3, v3, v46
	v_sub_f32_e32 v2, v2, v46
	v_pk_mul_f32 v[48:49], v[46:47], v[2:3] op_sel:[1,0]
	v_pk_mul_f32 v[2:3], v[46:47], v[4:5] op_sel:[1,0]
	s_waitcnt vmcnt(0)
	v_pk_fma_f32 v[46:47], v[14:15], v[48:49], v[22:23]
	v_pk_fma_f32 v[2:3], v[16:17], v[2:3], v[24:25]
	s_cbranch_vccnz .LBB0_634
	v_pk_fma_f32 v[4:5], v[64:65], v[2:3], v[32:33]
	v_pk_fma_f32 v[48:49], v[62:63], v[46:47], v[30:31]
	s_nop 0
	v_cvt_pk_bf16_f32 v48, v48, v49
	v_cvt_pk_bf16_f32 v4, v4, v5
	s_nop 0
	v_cndmask_b32_e64 v5, v4, v221, s[40:41]
	v_cndmask_b32_e64 v4, v48, v221, s[40:41]
	v_lshl_add_u64 v[48:49], v[160:161], 1, v[176:177]
	global_store_dwordx2 v[48:49], v[4:5], off offset:288
.LBB0_634:
	v_mov_b64_e32 v[4:5], v[228:229]
	s_and_b64 vcc, exec, s[38:39]
	s_waitcnt lgkmcnt(0)
	v_sub_f32_e32 v9, v9, v4
	v_sub_f32_e32 v8, v8, v4
	v_sub_f32_e32 v7, v7, v4
	v_sub_f32_e32 v6, v6, v4
	v_pk_mul_f32 v[6:7], v[4:5], v[6:7] op_sel:[1,0]
	v_pk_mul_f32 v[4:5], v[4:5], v[8:9] op_sel:[1,0]
	v_pk_fma_f32 v[6:7], v[14:15], v[6:7], v[22:23]
	v_pk_fma_f32 v[4:5], v[16:17], v[4:5], v[24:25]
	s_cbranch_vccnz .LBB0_636
	v_pk_fma_f32 v[8:9], v[64:65], v[4:5], v[32:33]
	v_pk_fma_f32 v[48:49], v[62:63], v[6:7], v[30:31]
	s_nop 0
	v_cvt_pk_bf16_f32 v48, v48, v49
	v_cvt_pk_bf16_f32 v8, v8, v9
	s_nop 0
	v_cndmask_b32_e64 v9, v8, v221, s[40:41]
	v_cndmask_b32_e64 v8, v48, v221, s[40:41]
	v_lshl_add_u64 v[48:49], v[160:161], 1, v[182:183]
	global_store_dwordx2 v[48:49], v[8:9], off offset:288
.LBB0_636:
	v_mov_b64_e32 v[8:9], v[230:231]
	s_and_b64 vcc, exec, s[38:39]
	s_waitcnt lgkmcnt(0)
	v_sub_f32_e32 v13, v13, v8
	v_sub_f32_e32 v12, v12, v8
	v_sub_f32_e32 v11, v11, v8
	v_sub_f32_e32 v10, v10, v8
	v_pk_mul_f32 v[10:11], v[8:9], v[10:11] op_sel:[1,0]
	v_pk_mul_f32 v[8:9], v[8:9], v[12:13] op_sel:[1,0]
	v_pk_fma_f32 v[12:13], v[14:15], v[10:11], v[22:23]
	v_pk_fma_f32 v[8:9], v[16:17], v[8:9], v[24:25]
	s_cbranch_vccnz .LBB0_638
	v_pk_fma_f32 v[10:11], v[64:65], v[8:9], v[32:33]
	v_pk_fma_f32 v[48:49], v[62:63], v[12:13], v[30:31]
	s_nop 0
	v_cvt_pk_bf16_f32 v48, v48, v49
	v_cvt_pk_bf16_f32 v10, v10, v11
	s_nop 0
	v_cndmask_b32_e64 v11, v10, v221, s[40:41]
	v_cndmask_b32_e64 v10, v48, v221, s[40:41]
	v_lshl_add_u64 v[48:49], v[160:161], 1, v[184:185]
	global_store_dwordx2 v[48:49], v[10:11], off offset:288
.LBB0_638:
	v_mov_b64_e32 v[10:11], v[232:233]
	s_and_b64 vcc, exec, s[38:39]
	s_waitcnt lgkmcnt(0)
	v_sub_f32_e32 v21, v21, v10
	v_sub_f32_e32 v20, v20, v10
	v_sub_f32_e32 v19, v19, v10
	v_sub_f32_e32 v18, v18, v10
	v_pk_mul_f32 v[18:19], v[10:11], v[18:19] op_sel:[1,0]
	v_pk_mul_f32 v[10:11], v[10:11], v[20:21] op_sel:[1,0]
	v_pk_fma_f32 v[18:19], v[14:15], v[18:19], v[22:23]
	v_pk_fma_f32 v[10:11], v[16:17], v[10:11], v[24:25]
	s_cbranch_vccnz .LBB0_640
	v_pk_fma_f32 v[20:21], v[64:65], v[10:11], v[32:33]
	v_pk_fma_f32 v[48:49], v[62:63], v[18:19], v[30:31]
	s_nop 0
	v_cvt_pk_bf16_f32 v48, v48, v49
	v_cvt_pk_bf16_f32 v20, v20, v21
	s_nop 0
	v_cndmask_b32_e64 v21, v20, v221, s[40:41]
	v_cndmask_b32_e64 v20, v48, v221, s[40:41]
	v_lshl_add_u64 v[48:49], v[160:161], 1, v[200:201]
	global_store_dwordx2 v[48:49], v[20:21], off offset:288
.LBB0_640:
	v_mov_b64_e32 v[20:21], v[234:235]
	s_and_b64 vcc, exec, s[38:39]
	s_waitcnt lgkmcnt(0)
	v_sub_f32_e32 v29, v29, v20
	v_sub_f32_e32 v28, v28, v20
	v_sub_f32_e32 v27, v27, v20
	v_sub_f32_e32 v26, v26, v20
	v_pk_mul_f32 v[26:27], v[20:21], v[26:27] op_sel:[1,0]
	v_pk_mul_f32 v[20:21], v[20:21], v[28:29] op_sel:[1,0]
	v_pk_fma_f32 v[28:29], v[14:15], v[26:27], v[22:23]
	v_pk_fma_f32 v[20:21], v[16:17], v[20:21], v[24:25]
	s_cbranch_vccnz .LBB0_642
	v_pk_fma_f32 v[26:27], v[64:65], v[20:21], v[32:33]
	v_pk_fma_f32 v[48:49], v[62:63], v[28:29], v[30:31]
	s_nop 0
	v_cvt_pk_bf16_f32 v48, v48, v49
	v_cvt_pk_bf16_f32 v26, v26, v27
	s_nop 0
	v_cndmask_b32_e64 v27, v26, v221, s[40:41]
	v_cndmask_b32_e64 v26, v48, v221, s[40:41]
	v_lshl_add_u64 v[48:49], v[160:161], 1, v[202:203]
	global_store_dwordx2 v[48:49], v[26:27], off offset:288
.LBB0_642:
	v_mov_b64_e32 v[26:27], v[236:237]
	s_and_b64 vcc, exec, s[38:39]
	s_waitcnt lgkmcnt(0)
	v_sub_f32_e32 v41, v41, v26
	v_sub_f32_e32 v40, v40, v26
	v_sub_f32_e32 v39, v39, v26
	v_sub_f32_e32 v38, v38, v26
	v_pk_mul_f32 v[38:39], v[26:27], v[38:39] op_sel:[1,0]
	v_pk_mul_f32 v[26:27], v[26:27], v[40:41] op_sel:[1,0]
	v_pk_fma_f32 v[38:39], v[14:15], v[38:39], v[22:23]
	v_pk_fma_f32 v[26:27], v[16:17], v[26:27], v[24:25]
	s_cbranch_vccnz .LBB0_644
	v_pk_fma_f32 v[40:41], v[64:65], v[26:27], v[32:33]
	v_pk_fma_f32 v[48:49], v[62:63], v[38:39], v[30:31]
	s_nop 0
	v_cvt_pk_bf16_f32 v48, v48, v49
	v_cvt_pk_bf16_f32 v40, v40, v41
	s_nop 0
	v_cndmask_b32_e64 v41, v40, v221, s[40:41]
	v_cndmask_b32_e64 v40, v48, v221, s[40:41]
	v_lshl_add_u64 v[48:49], v[160:161], 1, v[204:205]
	global_store_dwordx2 v[48:49], v[40:41], off offset:288
.LBB0_644:
	v_mov_b64_e32 v[40:41], v[238:239]
	s_and_b64 vcc, exec, s[38:39]
	s_waitcnt lgkmcnt(0)
	v_sub_f32_e32 v49, v57, v40
	v_sub_f32_e32 v48, v56, v40
	v_sub_f32_e32 v55, v55, v40
	v_sub_f32_e32 v54, v54, v40
	v_pk_mul_f32 v[54:55], v[40:41], v[54:55] op_sel:[1,0]
	v_pk_mul_f32 v[40:41], v[40:41], v[48:49] op_sel:[1,0]
	v_pk_fma_f32 v[48:49], v[14:15], v[54:55], v[22:23]
	v_pk_fma_f32 v[40:41], v[16:17], v[40:41], v[24:25]
	s_cbranch_vccnz .LBB0_646
	v_pk_fma_f32 v[54:55], v[64:65], v[40:41], v[32:33]
	v_pk_fma_f32 v[56:57], v[62:63], v[48:49], v[30:31]
	s_nop 0
	v_cvt_pk_bf16_f32 v56, v56, v57
	v_cvt_pk_bf16_f32 v54, v54, v55
	s_nop 0
	v_cndmask_b32_e64 v55, v54, v221, s[40:41]
	v_cndmask_b32_e64 v54, v56, v221, s[40:41]
	v_lshl_add_u64 v[56:57], v[160:161], 1, v[206:207]
	global_store_dwordx2 v[56:57], v[54:55], off offset:288
.LBB0_646:
	v_mov_b64_e32 v[54:55], v[240:241]
	s_and_b64 vcc, exec, s[38:39]
	s_waitcnt lgkmcnt(0)
	v_sub_f32_e32 v53, v53, v54
	v_sub_f32_e32 v52, v52, v54
	v_sub_f32_e32 v51, v51, v54
	v_sub_f32_e32 v50, v50, v54
	v_pk_mul_f32 v[50:51], v[54:55], v[50:51] op_sel:[1,0]
	v_pk_mul_f32 v[52:53], v[54:55], v[52:53] op_sel:[1,0]
	v_pk_fma_f32 v[14:15], v[14:15], v[50:51], v[22:23]
	v_pk_fma_f32 v[16:17], v[16:17], v[52:53], v[24:25]
	s_cbranch_vccnz .LBB0_650
	v_pk_fma_f32 v[22:23], v[64:65], v[16:17], v[32:33]
	v_pk_fma_f32 v[24:25], v[62:63], v[14:15], v[30:31]
	v_readlane_b32 s0, v251, 11
	v_cvt_pk_bf16_f32 v24, v24, v25
	v_cvt_pk_bf16_f32 v22, v22, v23
	v_readlane_b32 s1, v251, 12
	v_cndmask_b32_e64 v23, v22, v221, s[40:41]
	v_cndmask_b32_e64 v22, v24, v221, s[40:41]
	v_lshl_add_u64 v[24:25], v[160:161], 1, v[208:209]
	global_store_dwordx2 v[24:25], v[22:23], off offset:288
	v_mov_b32_e32 v22, v0
	s_and_b64 vcc, exec, s[0:1]
	s_cbranch_vccz .LBB0_650
	v_lshlrev_b32_e32 v23, 4, v22
	v_readlane_b32 s8, v251, 16
	v_and_b32_e32 v24, 0xfffffc00, v23
	s_add_u32 s0, s56, 0x1300000
	v_ashrrev_i32_e32 v23, 31, v22
	v_readlane_b32 s9, v251, 17
	v_readlane_b32 s10, v251, 25
	s_addc_u32 s1, s57, 0
	v_lshl_add_u64 v[22:23], v[22:23], 4, s[8:9]
	s_mov_b64 s[8:9], 0
	v_add_u32_e32 v24, s10, v24

.LBB0_3284:
	s_or_b64 exec, exec, s[8:9]
	s_add_u32 s0, s6, 0x3400000
	s_addc_u32 s1, s7, 0
	s_add_u32 s42, s48, 0x1000
	s_addc_u32 s43, s49, 0
	s_add_u32 s44, s50, 0x1000
	s_waitcnt lgkmcnt(0)
	v_cmp_ne_u32_e32 vcc, 0, v131
	s_addc_u32 s45, s51, 0
	s_or_b64 s[40:41], vcc, s[46:47]
	s_add_u32 s8, s6, s52
	s_addc_u32 s9, s7, s53
	v_lshl_add_u64 v[142:143], s[8:9], 0, v[164:165]
	s_mov_b64 s[8:9], 0x107000
	v_lshl_add_u64 v[174:175], v[142:143], 0, s[8:9]
	s_mov_b64 s[8:9], 0x106000
	v_lshl_add_u64 v[172:173], v[142:143], 0, s[8:9]
	s_mov_b32 s8, 0x107000
	v_add_co_u32_e32 v138, vcc, s8, v142
	s_waitcnt lgkmcnt(0)
	s_barrier
	s_nop 0
	v_addc_co_u32_e32 v139, vcc, 0, v143, vcc
	global_load_dwordx4 v[138:141], v[138:139], off
	s_mov_b32 s8, 0x106000
	v_lshl_add_u64 v[130:131], s[42:43], 0, v[164:165]
	v_lshl_add_u64 v[134:135], s[44:45], 0, v[164:165]
	global_load_dwordx4 v[130:133], v[130:131], off
	v_lshl_add_u32 v188, v166, 3, 0
	global_load_dwordx4 v[134:137], v[134:135], off
	v_add_u32_e32 v184, s19, v166
	v_ashrrev_i32_e32 v185, 31, v184
	v_lshlrev_b64 v[206:207], 1, v[162:163]
	s_waitcnt vmcnt(0)
	v_pk_add_f32 v[170:171], v[138:139], 1.0 op_sel_hi:[1,0]
	v_add_co_u32_e32 v138, vcc, s8, v142
	v_pk_add_f32 v[168:169], v[140:141], 1.0 op_sel_hi:[1,0]
	s_nop 0
	v_addc_co_u32_e32 v139, vcc, 0, v143, vcc
	global_load_dwordx4 v[138:141], v[138:139], off
	ds_read_b64 v[226:227], v188 offset:8192
	ds_read_b64 v[228:229], v188 offset:8320
	ds_read_b64 v[230:231], v188 offset:8448
	ds_read_b64 v[232:233], v188 offset:8576
	ds_read_b64 v[234:235], v188 offset:9216
	ds_read_b64 v[236:237], v188 offset:9344
	ds_read_b64 v[238:239], v188 offset:9472
	ds_read_b64 v[240:241], v188 offset:9600
	s_waitcnt lgkmcnt(0)
	v_mov_b64_e32 v[142:143], v[226:227]
	s_waitcnt lgkmcnt(0)
	v_sub_f32_e32 v127, v127, v142
	v_sub_f32_e32 v126, v126, v142
	v_sub_f32_e32 v129, v129, v142
	v_sub_f32_e32 v128, v128, v142
	v_pk_mul_f32 v[126:127], v[142:143], v[126:127] op_sel:[1,0]
	v_pk_mul_f32 v[128:129], v[142:143], v[128:129] op_sel:[1,0]
	v_pk_fma_f32 v[126:127], v[130:131], v[126:127], v[134:135]
	v_pk_fma_f32 v[128:129], v[132:133], v[128:129], v[136:137]
	s_waitcnt vmcnt(0)
	v_pk_fma_f32 v[144:145], v[170:171], v[126:127], v[138:139]
	v_pk_fma_f32 v[142:143], v[168:169], v[128:129], v[140:141]
	v_cvt_pk_bf16_f32 v144, v144, v145
	s_nop 0
	v_cvt_pk_bf16_f32 v143, v142, v143
	v_cndmask_b32_e64 v142, v144, v221, s[40:41]
	v_lshlrev_b64 v[144:145], 11, v[184:185]
	v_lshl_add_u64 v[144:145], s[0:1], 0, v[144:145]
	v_cndmask_b32_e64 v143, v143, v221, s[40:41]
	v_lshl_add_u64 v[178:179], v[144:145], 0, v[206:207]
	global_store_dwordx2 v[178:179], v[142:143], off
	v_mov_b64_e32 v[142:143], v[228:229]
	v_add_u32_e32 v144, 16, v184
	v_ashrrev_i32_e32 v145, 31, v144
	v_lshlrev_b64 v[144:145], 11, v[144:145]
	v_lshl_add_u64 v[144:145], s[0:1], 0, v[144:145]
	s_waitcnt lgkmcnt(0)
	v_sub_f32_e32 v125, v125, v142
	v_sub_f32_e32 v124, v124, v142
	v_sub_f32_e32 v123, v123, v142
	v_sub_f32_e32 v122, v122, v142
	v_pk_mul_f32 v[124:125], v[142:143], v[124:125] op_sel:[1,0]
	v_pk_mul_f32 v[122:123], v[142:143], v[122:123] op_sel:[1,0]
	v_pk_fma_f32 v[124:125], v[132:133], v[124:125], v[136:137]
	v_pk_fma_f32 v[122:123], v[130:131], v[122:123], v[134:135]
	v_pk_fma_f32 v[142:143], v[168:169], v[124:125], v[140:141]
	v_pk_fma_f32 v[164:165], v[170:171], v[122:123], v[138:139]
	v_lshl_add_u64 v[176:177], v[144:145], 0, v[206:207]
	v_cvt_pk_bf16_f32 v163, v164, v165
	v_cvt_pk_bf16_f32 v143, v142, v143
	v_add_u32_e32 v144, 32, v184
	v_cndmask_b32_e64 v142, v163, v221, s[40:41]
	v_cndmask_b32_e64 v143, v143, v221, s[40:41]
	global_store_dwordx2 v[176:177], v[142:143], off
	v_mov_b64_e32 v[142:143], v[230:231]
	v_ashrrev_i32_e32 v145, 31, v144
	v_lshlrev_b64 v[144:145], 11, v[144:145]
	v_lshl_add_u64 v[144:145], s[0:1], 0, v[144:145]
	v_lshl_add_u64 v[180:181], v[144:145], 0, v[206:207]
	s_waitcnt lgkmcnt(0)
	v_sub_f32_e32 v121, v121, v142
	v_sub_f32_e32 v120, v120, v142
	v_sub_f32_e32 v119, v119, v142
	v_sub_f32_e32 v118, v118, v142
	v_pk_mul_f32 v[120:121], v[142:143], v[120:121] op_sel:[1,0]
	v_pk_mul_f32 v[118:119], v[142:143], v[118:119] op_sel:[1,0]
	v_pk_fma_f32 v[120:121], v[132:133], v[120:121], v[136:137]
	v_pk_fma_f32 v[118:119], v[130:131], v[118:119], v[134:135]
	v_pk_fma_f32 v[142:143], v[168:169], v[120:121], v[140:141]
	v_pk_fma_f32 v[164:165], v[170:171], v[118:119], v[138:139]
	v_add_u32_e32 v144, 48, v184
	v_cvt_pk_bf16_f32 v163, v164, v165
	v_cvt_pk_bf16_f32 v143, v142, v143
	v_ashrrev_i32_e32 v145, 31, v144
	v_cndmask_b32_e64 v142, v163, v221, s[40:41]
	v_cndmask_b32_e64 v143, v143, v221, s[40:41]
	global_store_dwordx2 v[180:181], v[142:143], off
	v_mov_b64_e32 v[142:143], v[232:233]
	v_lshlrev_b64 v[144:145], 11, v[144:145]
	v_lshl_add_u64 v[144:145], s[0:1], 0, v[144:145]
	v_lshl_add_u64 v[182:183], v[144:145], 0, v[206:207]
	s_waitcnt lgkmcnt(0)
	v_sub_f32_e32 v117, v117, v142
	v_sub_f32_e32 v116, v116, v142
	v_sub_f32_e32 v115, v115, v142
	v_sub_f32_e32 v114, v114, v142
	v_pk_mul_f32 v[116:117], v[142:143], v[116:117] op_sel:[1,0]
	v_pk_mul_f32 v[114:115], v[142:143], v[114:115] op_sel:[1,0]
	v_pk_fma_f32 v[116:117], v[132:133], v[116:117], v[136:137]
	v_pk_fma_f32 v[114:115], v[130:131], v[114:115], v[134:135]
	v_pk_fma_f32 v[142:143], v[168:169], v[116:117], v[140:141]
	v_pk_fma_f32 v[164:165], v[170:171], v[114:115], v[138:139]
	s_nop 0
	v_cvt_pk_bf16_f32 v163, v164, v165
	v_cvt_pk_bf16_f32 v143, v142, v143
	v_add_u32_e32 v164, 0x80, v184
	v_cndmask_b32_e64 v142, v163, v221, s[40:41]
	v_cndmask_b32_e64 v143, v143, v221, s[40:41]
	global_store_dwordx2 v[182:183], v[142:143], off
	v_mov_b64_e32 v[142:143], v[234:235]
	v_ashrrev_i32_e32 v165, 31, v164
	s_waitcnt lgkmcnt(0)
	v_sub_f32_e32 v107, v107, v142
	v_sub_f32_e32 v106, v106, v142
	v_sub_f32_e32 v109, v109, v142
	v_sub_f32_e32 v108, v108, v142
	v_pk_mul_f32 v[106:107], v[142:143], v[106:107] op_sel:[1,0]
	v_pk_mul_f32 v[108:109], v[142:143], v[108:109] op_sel:[1,0]
	v_pk_fma_f32 v[142:143], v[130:131], v[106:107], v[134:135]
	v_pk_fma_f32 v[144:145], v[132:133], v[108:109], v[136:137]
	v_pk_fma_f32 v[108:109], v[170:171], v[142:143], v[138:139]
	v_pk_fma_f32 v[106:107], v[168:169], v[144:145], v[140:141]
	v_cvt_pk_bf16_f32 v108, v108, v109
	s_nop 0
	v_cvt_pk_bf16_f32 v107, v106, v107
	v_cndmask_b32_e64 v106, v108, v221, s[40:41]
	v_lshlrev_b64 v[108:109], 11, v[164:165]
	v_lshl_add_u64 v[108:109], s[0:1], 0, v[108:109]
	v_cndmask_b32_e64 v107, v107, v221, s[40:41]
	v_lshl_add_u64 v[204:205], v[108:109], 0, v[206:207]
	global_store_dwordx2 v[204:205], v[106:107], off
	v_mov_b64_e32 v[106:107], v[236:237]
	v_add_u32_e32 v108, 0x90, v184
	v_ashrrev_i32_e32 v109, 31, v108
	v_lshlrev_b64 v[108:109], 11, v[108:109]
	v_lshl_add_u64 v[108:109], s[0:1], 0, v[108:109]
	s_waitcnt lgkmcnt(0)
	v_sub_f32_e32 v113, v113, v106
	v_sub_f32_e32 v112, v112, v106
	v_sub_f32_e32 v111, v111, v106
	v_sub_f32_e32 v110, v110, v106
	v_pk_mul_f32 v[110:111], v[106:107], v[110:111] op_sel:[1,0]
	v_pk_mul_f32 v[106:107], v[106:107], v[112:113] op_sel:[1,0]
	v_pk_fma_f32 v[110:111], v[130:131], v[110:111], v[134:135]
	v_pk_fma_f32 v[112:113], v[132:133], v[106:107], v[136:137]
	v_pk_fma_f32 v[164:165], v[170:171], v[110:111], v[138:139]
	v_pk_fma_f32 v[106:107], v[168:169], v[112:113], v[140:141]
	v_cvt_pk_bf16_f32 v163, v164, v165
	v_lshl_add_u64 v[202:203], v[108:109], 0, v[206:207]
	v_cvt_pk_bf16_f32 v107, v106, v107
	v_cndmask_b32_e64 v106, v163, v221, s[40:41]
	v_cndmask_b32_e64 v107, v107, v221, s[40:41]
	global_store_dwordx2 v[202:203], v[106:107], off
	v_mov_b64_e32 v[106:107], v[238:239]
	v_add_u32_e32 v108, 0xa0, v184
	v_ashrrev_i32_e32 v109, 31, v108
	s_waitcnt lgkmcnt(0)
	v_sub_f32_e32 v103, v103, v106
	v_sub_f32_e32 v102, v102, v106
	v_sub_f32_e32 v105, v105, v106
	v_sub_f32_e32 v104, v104, v106
	v_pk_mul_f32 v[102:103], v[106:107], v[102:103] op_sel:[1,0]
	v_pk_mul_f32 v[104:105], v[106:107], v[104:105] op_sel:[1,0]
	v_pk_fma_f32 v[164:165], v[130:131], v[102:103], v[134:135]
	v_pk_fma_f32 v[166:167], v[132:133], v[104:105], v[136:137]
	v_pk_fma_f32 v[104:105], v[170:171], v[164:165], v[138:139]
	v_pk_fma_f32 v[102:103], v[168:169], v[166:167], v[140:141]
	v_cvt_pk_bf16_f32 v104, v104, v105
	s_nop 0
	v_cvt_pk_bf16_f32 v103, v102, v103
	v_cndmask_b32_e64 v102, v104, v221, s[40:41]
	v_lshlrev_b64 v[104:105], 11, v[108:109]
	v_lshl_add_u64 v[104:105], s[0:1], 0, v[104:105]
	v_cndmask_b32_e64 v103, v103, v221, s[40:41]
	v_lshl_add_u64 v[200:201], v[104:105], 0, v[206:207]
	global_store_dwordx2 v[200:201], v[102:103], off
	v_mov_b64_e32 v[102:103], v[240:241]
	v_add_u32_e32 v104, 0xb0, v184
	v_ashrrev_i32_e32 v105, 31, v104
	s_waitcnt lgkmcnt(0)
	v_sub_f32_e32 v99, v99, v102
	v_sub_f32_e32 v98, v98, v102
	v_sub_f32_e32 v101, v101, v102
	v_sub_f32_e32 v100, v100, v102
	v_pk_mul_f32 v[98:99], v[102:103], v[98:99] op_sel:[1,0]
	v_pk_mul_f32 v[100:101], v[102:103], v[100:101] op_sel:[1,0]
	v_pk_fma_f32 v[130:131], v[130:131], v[98:99], v[134:135]
	v_pk_fma_f32 v[132:133], v[132:133], v[100:101], v[136:137]
	v_pk_fma_f32 v[100:101], v[170:171], v[130:131], v[138:139]
	v_pk_fma_f32 v[98:99], v[168:169], v[132:133], v[140:141]
	v_cvt_pk_bf16_f32 v100, v100, v101
	s_nop 0
	v_cvt_pk_bf16_f32 v99, v98, v99
	v_cndmask_b32_e64 v98, v100, v221, s[40:41]
	v_lshlrev_b64 v[100:101], 11, v[104:105]
	v_lshl_add_u64 v[100:101], s[0:1], 0, v[100:101]
	v_cndmask_b32_e64 v99, v99, v221, s[40:41]
	v_lshl_add_u64 v[184:185], v[100:101], 0, v[206:207]
	global_store_dwordx2 v[184:185], v[98:99], off
	v_or_b32_e32 v98, 16, v162
	v_ashrrev_i32_e32 v99, 31, v98
	v_lshlrev_b64 v[102:103], 2, v[98:99]
	v_lshl_add_u64 v[98:99], s[42:43], 0, v[102:103]
	v_lshl_add_u64 v[102:103], s[44:45], 0, v[102:103]
	global_load_dwordx4 v[98:101], v[98:99], off
	s_nop 0
	global_load_dwordx4 v[102:105], v[102:103], off
	s_nop 0
	global_load_dwordx4 v[106:109], v[174:175], off offset:64
	v_mov_b64_e32 v[134:135], v[226:227]
	v_readlane_b32 s0, v251, 13
	v_readlane_b32 s1, v251, 14
	s_andn2_b64 vcc, exec, s[0:1]
	s_waitcnt lgkmcnt(0)
	v_sub_f32_e32 v69, v69, v134
	v_sub_f32_e32 v68, v68, v134
	v_sub_f32_e32 v67, v67, v134
	v_sub_f32_e32 v66, v66, v134
	v_pk_mul_f32 v[66:67], v[134:135], v[66:67] op_sel:[1,0]
	v_pk_mul_f32 v[68:69], v[134:135], v[68:69] op_sel:[1,0]
	s_waitcnt vmcnt(1)
	v_pk_fma_f32 v[134:135], v[98:99], v[66:67], v[102:103]
	s_waitcnt vmcnt(0)
	v_pk_add_f32 v[206:207], v[108:109], 1.0 op_sel_hi:[1,0]
	v_pk_add_f32 v[208:209], v[106:107], 1.0 op_sel_hi:[1,0]
	global_load_dwordx4 v[106:109], v[172:173], off offset:64
	v_pk_fma_f32 v[136:137], v[100:101], v[68:69], v[104:105]
	s_waitcnt vmcnt(0)
	v_pk_fma_f32 v[68:69], v[208:209], v[134:135], v[106:107]
	v_pk_fma_f32 v[66:67], v[206:207], v[136:137], v[108:109]
	v_cvt_pk_bf16_f32 v68, v68, v69
	s_nop 0
	v_cvt_pk_bf16_f32 v66, v66, v67
	s_nop 0
	v_cndmask_b32_e64 v67, v66, v221, s[40:41]
	v_cndmask_b32_e64 v66, v68, v221, s[40:41]
	global_store_dwordx2 v[178:179], v[66:67], off offset:32
	v_mov_b64_e32 v[66:67], v[228:229]
	s_waitcnt lgkmcnt(0)
	v_sub_f32_e32 v69, v73, v66
	v_sub_f32_e32 v68, v72, v66
	v_sub_f32_e32 v71, v71, v66
	v_sub_f32_e32 v70, v70, v66
	v_pk_mul_f32 v[70:71], v[66:67], v[70:71] op_sel:[1,0]
	v_pk_mul_f32 v[66:67], v[66:67], v[68:69] op_sel:[1,0]
	v_pk_fma_f32 v[138:139], v[98:99], v[70:71], v[102:103]
	v_pk_fma_f32 v[140:141], v[100:101], v[66:67], v[104:105]
	v_pk_fma_f32 v[68:69], v[208:209], v[138:139], v[106:107]
	v_pk_fma_f32 v[66:67], v[206:207], v[140:141], v[108:109]
	v_cvt_pk_bf16_f32 v68, v68, v69
	s_nop 0
	v_cvt_pk_bf16_f32 v66, v66, v67
	s_nop 0
	v_cndmask_b32_e64 v67, v66, v221, s[40:41]
	v_cndmask_b32_e64 v66, v68, v221, s[40:41]
	global_store_dwordx2 v[176:177], v[66:67], off offset:32
	v_mov_b64_e32 v[66:67], v[230:231]
	s_waitcnt lgkmcnt(0)
	v_sub_f32_e32 v69, v77, v66
	v_sub_f32_e32 v68, v76, v66
	v_sub_f32_e32 v71, v75, v66
	v_sub_f32_e32 v70, v74, v66
	v_pk_mul_f32 v[70:71], v[66:67], v[70:71] op_sel:[1,0]
	v_pk_mul_f32 v[66:67], v[66:67], v[68:69] op_sel:[1,0]
	v_pk_fma_f32 v[168:169], v[98:99], v[70:71], v[102:103]
	v_pk_fma_f32 v[170:171], v[100:101], v[66:67], v[104:105]
	v_pk_fma_f32 v[68:69], v[208:209], v[168:169], v[106:107]
	v_pk_fma_f32 v[66:67], v[206:207], v[170:171], v[108:109]
	v_cvt_pk_bf16_f32 v68, v68, v69
	s_nop 0
	v_cvt_pk_bf16_f32 v66, v66, v67
	s_nop 0
	v_cndmask_b32_e64 v67, v66, v221, s[40:41]
	v_cndmask_b32_e64 v66, v68, v221, s[40:41]
	global_store_dwordx2 v[180:181], v[66:67], off offset:32
	v_mov_b64_e32 v[66:67], v[232:233]
	s_waitcnt lgkmcnt(0)
	v_sub_f32_e32 v69, v81, v66
	v_sub_f32_e32 v68, v80, v66
	v_sub_f32_e32 v71, v79, v66
	v_sub_f32_e32 v70, v78, v66
	v_pk_mul_f32 v[70:71], v[66:67], v[70:71] op_sel:[1,0]
	v_pk_mul_f32 v[66:67], v[66:67], v[68:69] op_sel:[1,0]
	v_pk_fma_f32 v[78:79], v[98:99], v[70:71], v[102:103]
	v_pk_fma_f32 v[80:81], v[100:101], v[66:67], v[104:105]
	v_pk_fma_f32 v[68:69], v[208:209], v[78:79], v[106:107]
	v_pk_fma_f32 v[66:67], v[206:207], v[80:81], v[108:109]
	v_cvt_pk_bf16_f32 v68, v68, v69
	s_nop 0
	v_cvt_pk_bf16_f32 v66, v66, v67
	s_nop 0
	v_cndmask_b32_e64 v67, v66, v221, s[40:41]
	v_cndmask_b32_e64 v66, v68, v221, s[40:41]
	global_store_dwordx2 v[182:183], v[66:67], off offset:32
	v_mov_b64_e32 v[66:67], v[234:235]
	s_waitcnt lgkmcnt(0)
	v_sub_f32_e32 v69, v85, v66
	v_sub_f32_e32 v68, v84, v66
	v_sub_f32_e32 v71, v83, v66
	v_sub_f32_e32 v70, v82, v66
	v_pk_mul_f32 v[70:71], v[66:67], v[70:71] op_sel:[1,0]
	v_pk_mul_f32 v[66:67], v[66:67], v[68:69] op_sel:[1,0]
	v_pk_fma_f32 v[82:83], v[98:99], v[70:71], v[102:103]
	v_pk_fma_f32 v[84:85], v[100:101], v[66:67], v[104:105]
	v_pk_fma_f32 v[68:69], v[208:209], v[82:83], v[106:107]
	v_pk_fma_f32 v[66:67], v[206:207], v[84:85], v[108:109]
	v_cvt_pk_bf16_f32 v68, v68, v69
	s_nop 0
	v_cvt_pk_bf16_f32 v66, v66, v67
	s_nop 0
	v_cndmask_b32_e64 v67, v66, v221, s[40:41]
	v_cndmask_b32_e64 v66, v68, v221, s[40:41]
	global_store_dwordx2 v[204:205], v[66:67], off offset:32
	v_mov_b64_e32 v[66:67], v[236:237]
	s_waitcnt lgkmcnt(0)
	v_sub_f32_e32 v69, v89, v66
	v_sub_f32_e32 v68, v88, v66
	v_sub_f32_e32 v71, v87, v66
	v_sub_f32_e32 v70, v86, v66
	v_pk_mul_f32 v[70:71], v[66:67], v[70:71] op_sel:[1,0]
	v_pk_mul_f32 v[66:67], v[66:67], v[68:69] op_sel:[1,0]
	v_pk_fma_f32 v[86:87], v[98:99], v[70:71], v[102:103]
	v_pk_fma_f32 v[88:89], v[100:101], v[66:67], v[104:105]
	v_pk_fma_f32 v[68:69], v[208:209], v[86:87], v[106:107]
	v_pk_fma_f32 v[66:67], v[206:207], v[88:89], v[108:109]
	v_cvt_pk_bf16_f32 v68, v68, v69
	s_nop 0
	v_cvt_pk_bf16_f32 v66, v66, v67
	s_nop 0
	v_cndmask_b32_e64 v67, v66, v221, s[40:41]
	v_cndmask_b32_e64 v66, v68, v221, s[40:41]
	global_store_dwordx2 v[202:203], v[66:67], off offset:32
	v_mov_b64_e32 v[66:67], v[238:239]
	s_waitcnt lgkmcnt(0)
	v_sub_f32_e32 v69, v93, v66
	v_sub_f32_e32 v68, v92, v66
	v_sub_f32_e32 v71, v91, v66
	v_sub_f32_e32 v70, v90, v66
	v_pk_mul_f32 v[70:71], v[66:67], v[70:71] op_sel:[1,0]
	v_pk_mul_f32 v[66:67], v[66:67], v[68:69] op_sel:[1,0]
	v_pk_fma_f32 v[90:91], v[98:99], v[70:71], v[102:103]
	v_pk_fma_f32 v[92:93], v[100:101], v[66:67], v[104:105]
	v_pk_fma_f32 v[68:69], v[208:209], v[90:91], v[106:107]
	v_pk_fma_f32 v[66:67], v[206:207], v[92:93], v[108:109]
	v_cvt_pk_bf16_f32 v68, v68, v69
	s_nop 0
	v_cvt_pk_bf16_f32 v66, v66, v67
	s_nop 0
	v_cndmask_b32_e64 v67, v66, v221, s[40:41]
	v_cndmask_b32_e64 v66, v68, v221, s[40:41]
	global_store_dwordx2 v[200:201], v[66:67], off offset:32
	v_mov_b64_e32 v[66:67], v[240:241]
	s_waitcnt lgkmcnt(0)
	v_sub_f32_e32 v69, v97, v66
	v_sub_f32_e32 v68, v96, v66
	v_sub_f32_e32 v71, v95, v66
	v_sub_f32_e32 v70, v94, v66
	v_pk_mul_f32 v[70:71], v[66:67], v[70:71] op_sel:[1,0]
	v_pk_mul_f32 v[66:67], v[66:67], v[68:69] op_sel:[1,0]
	v_pk_fma_f32 v[94:95], v[98:99], v[70:71], v[102:103]
	v_pk_fma_f32 v[96:97], v[100:101], v[66:67], v[104:105]
	v_pk_fma_f32 v[68:69], v[208:209], v[94:95], v[106:107]
	v_pk_fma_f32 v[66:67], v[206:207], v[96:97], v[108:109]
	v_cvt_pk_bf16_f32 v68, v68, v69
	s_nop 0
	v_cvt_pk_bf16_f32 v66, v66, v67
	s_nop 0
	v_cndmask_b32_e64 v67, v66, v221, s[40:41]
	v_cndmask_b32_e64 v66, v68, v221, s[40:41]
	global_store_dwordx2 v[184:185], v[66:67], off offset:32
	v_or_b32_e32 v66, 0x80, v162
	v_ashrrev_i32_e32 v67, 31, v66
	v_lshlrev_b64 v[70:71], 2, v[66:67]
	v_lshl_add_u64 v[66:67], s[42:43], 0, v[70:71]
	v_lshl_add_u64 v[70:71], s[44:45], 0, v[70:71]
	global_load_dwordx4 v[66:69], v[66:67], off
	s_nop 0
	global_load_dwordx4 v[70:73], v[70:71], off
	s_nop 0
	global_load_dwordx4 v[74:77], v[174:175], off offset:512
	v_mov_b64_e32 v[98:99], v[226:227]
	s_waitcnt lgkmcnt(0)
	v_sub_f32_e32 v37, v37, v98
	v_sub_f32_e32 v36, v36, v98
	v_sub_f32_e32 v35, v35, v98
	v_sub_f32_e32 v34, v34, v98
	v_pk_mul_f32 v[34:35], v[98:99], v[34:35] op_sel:[1,0]
	v_pk_mul_f32 v[36:37], v[98:99], v[36:37] op_sel:[1,0]
	s_waitcnt vmcnt(1)
	v_pk_fma_f32 v[98:99], v[66:67], v[34:35], v[70:71]
	s_waitcnt vmcnt(0)
	v_pk_add_f32 v[206:207], v[76:77], 1.0 op_sel_hi:[1,0]
	v_pk_add_f32 v[208:209], v[74:75], 1.0 op_sel_hi:[1,0]
	global_load_dwordx4 v[74:77], v[172:173], off offset:512
	v_pk_fma_f32 v[100:101], v[68:69], v[36:37], v[72:73]
	s_waitcnt vmcnt(0)
	v_pk_fma_f32 v[36:37], v[208:209], v[98:99], v[74:75]
	v_pk_fma_f32 v[34:35], v[206:207], v[100:101], v[76:77]
	v_cvt_pk_bf16_f32 v36, v36, v37
	s_nop 0
	v_cvt_pk_bf16_f32 v34, v34, v35
	s_nop 0
	v_cndmask_b32_e64 v35, v34, v221, s[40:41]
	v_cndmask_b32_e64 v34, v36, v221, s[40:41]
	global_store_dwordx2 v[178:179], v[34:35], off offset:256
	v_mov_b64_e32 v[34:35], v[228:229]
	s_waitcnt lgkmcnt(0)
	v_sub_f32_e32 v37, v41, v34
	v_sub_f32_e32 v36, v40, v34
	v_sub_f32_e32 v39, v39, v34
	v_sub_f32_e32 v38, v38, v34
	v_pk_mul_f32 v[38:39], v[34:35], v[38:39] op_sel:[1,0]
	v_pk_mul_f32 v[34:35], v[34:35], v[36:37] op_sel:[1,0]
	v_pk_fma_f32 v[102:103], v[66:67], v[38:39], v[70:71]
	v_pk_fma_f32 v[104:105], v[68:69], v[34:35], v[72:73]
	v_pk_fma_f32 v[36:37], v[208:209], v[102:103], v[74:75]
	v_pk_fma_f32 v[34:35], v[206:207], v[104:105], v[76:77]
	v_cvt_pk_bf16_f32 v36, v36, v37
	s_nop 0
	v_cvt_pk_bf16_f32 v34, v34, v35
	s_nop 0
	v_cndmask_b32_e64 v35, v34, v221, s[40:41]
	v_cndmask_b32_e64 v34, v36, v221, s[40:41]
	global_store_dwordx2 v[176:177], v[34:35], off offset:256
	v_mov_b64_e32 v[34:35], v[230:231]
	s_waitcnt lgkmcnt(0)
	v_sub_f32_e32 v37, v45, v34
	v_sub_f32_e32 v36, v44, v34
	v_sub_f32_e32 v39, v43, v34
	v_sub_f32_e32 v38, v42, v34
	v_pk_mul_f32 v[38:39], v[34:35], v[38:39] op_sel:[1,0]
	v_pk_mul_f32 v[34:35], v[34:35], v[36:37] op_sel:[1,0]
	v_pk_fma_f32 v[106:107], v[66:67], v[38:39], v[70:71]
	v_pk_fma_f32 v[108:109], v[68:69], v[34:35], v[72:73]
	v_pk_fma_f32 v[36:37], v[208:209], v[106:107], v[74:75]
	v_pk_fma_f32 v[34:35], v[206:207], v[108:109], v[76:77]
	v_cvt_pk_bf16_f32 v36, v36, v37
	s_nop 0
	v_cvt_pk_bf16_f32 v34, v34, v35
	s_nop 0
	v_cndmask_b32_e64 v35, v34, v221, s[40:41]
	v_cndmask_b32_e64 v34, v36, v221, s[40:41]
	global_store_dwordx2 v[180:181], v[34:35], off offset:256
	v_mov_b64_e32 v[34:35], v[232:233]
	s_waitcnt lgkmcnt(0)
	v_sub_f32_e32 v37, v49, v34
	v_sub_f32_e32 v36, v48, v34
	v_sub_f32_e32 v39, v47, v34
	v_sub_f32_e32 v38, v46, v34
	v_pk_mul_f32 v[38:39], v[34:35], v[38:39] op_sel:[1,0]
	v_pk_mul_f32 v[34:35], v[34:35], v[36:37] op_sel:[1,0]
	v_pk_fma_f32 v[46:47], v[66:67], v[38:39], v[70:71]
	v_pk_fma_f32 v[48:49], v[68:69], v[34:35], v[72:73]
	v_pk_fma_f32 v[36:37], v[208:209], v[46:47], v[74:75]
	v_pk_fma_f32 v[34:35], v[206:207], v[48:49], v[76:77]
	v_cvt_pk_bf16_f32 v36, v36, v37
	s_nop 0
	v_cvt_pk_bf16_f32 v34, v34, v35
	s_nop 0
	v_cndmask_b32_e64 v35, v34, v221, s[40:41]
	v_cndmask_b32_e64 v34, v36, v221, s[40:41]
	global_store_dwordx2 v[182:183], v[34:35], off offset:256
	v_mov_b64_e32 v[34:35], v[234:235]
	s_waitcnt lgkmcnt(0)
	v_sub_f32_e32 v37, v53, v34
	v_sub_f32_e32 v36, v52, v34
	v_sub_f32_e32 v39, v51, v34
	v_sub_f32_e32 v38, v50, v34
	v_pk_mul_f32 v[38:39], v[34:35], v[38:39] op_sel:[1,0]
	v_pk_mul_f32 v[34:35], v[34:35], v[36:37] op_sel:[1,0]
	v_pk_fma_f32 v[50:51], v[66:67], v[38:39], v[70:71]
	v_pk_fma_f32 v[52:53], v[68:69], v[34:35], v[72:73]
	v_pk_fma_f32 v[36:37], v[208:209], v[50:51], v[74:75]
	v_pk_fma_f32 v[34:35], v[206:207], v[52:53], v[76:77]
	v_cvt_pk_bf16_f32 v36, v36, v37
	s_nop 0
	v_cvt_pk_bf16_f32 v34, v34, v35
	s_nop 0
	v_cndmask_b32_e64 v35, v34, v221, s[40:41]
	v_cndmask_b32_e64 v34, v36, v221, s[40:41]
	global_store_dwordx2 v[204:205], v[34:35], off offset:256
	v_mov_b64_e32 v[34:35], v[236:237]
	s_waitcnt lgkmcnt(0)
	v_sub_f32_e32 v37, v57, v34
	v_sub_f32_e32 v36, v56, v34
	v_sub_f32_e32 v39, v55, v34
	v_sub_f32_e32 v38, v54, v34
	v_pk_mul_f32 v[38:39], v[34:35], v[38:39] op_sel:[1,0]
	v_pk_mul_f32 v[34:35], v[34:35], v[36:37] op_sel:[1,0]
	v_pk_fma_f32 v[54:55], v[66:67], v[38:39], v[70:71]
	v_pk_fma_f32 v[56:57], v[68:69], v[34:35], v[72:73]
	v_pk_fma_f32 v[36:37], v[208:209], v[54:55], v[74:75]
	v_pk_fma_f32 v[34:35], v[206:207], v[56:57], v[76:77]
	v_cvt_pk_bf16_f32 v36, v36, v37
	s_nop 0
	v_cvt_pk_bf16_f32 v34, v34, v35
	s_nop 0
	v_cndmask_b32_e64 v35, v34, v221, s[40:41]
	v_cndmask_b32_e64 v34, v36, v221, s[40:41]
	global_store_dwordx2 v[202:203], v[34:35], off offset:256
	v_mov_b64_e32 v[34:35], v[238:239]
	s_waitcnt lgkmcnt(0)
	v_sub_f32_e32 v37, v61, v34
	v_sub_f32_e32 v36, v60, v34
	v_sub_f32_e32 v39, v59, v34
	v_sub_f32_e32 v38, v58, v34
	v_pk_mul_f32 v[38:39], v[34:35], v[38:39] op_sel:[1,0]
	v_pk_mul_f32 v[34:35], v[34:35], v[36:37] op_sel:[1,0]
	v_pk_fma_f32 v[58:59], v[66:67], v[38:39], v[70:71]
	v_pk_fma_f32 v[60:61], v[68:69], v[34:35], v[72:73]
	v_pk_fma_f32 v[36:37], v[208:209], v[58:59], v[74:75]
	v_pk_fma_f32 v[34:35], v[206:207], v[60:61], v[76:77]
	v_cvt_pk_bf16_f32 v36, v36, v37
	s_nop 0
	v_cvt_pk_bf16_f32 v34, v34, v35
	s_nop 0
	v_cndmask_b32_e64 v35, v34, v221, s[40:41]
	v_cndmask_b32_e64 v34, v36, v221, s[40:41]
	global_store_dwordx2 v[200:201], v[34:35], off offset:256
	v_mov_b64_e32 v[34:35], v[240:241]
	s_waitcnt lgkmcnt(0)
	v_sub_f32_e32 v37, v65, v34
	v_sub_f32_e32 v36, v64, v34
	v_sub_f32_e32 v39, v63, v34
	v_sub_f32_e32 v38, v62, v34
	v_pk_mul_f32 v[38:39], v[34:35], v[38:39] op_sel:[1,0]
	v_pk_mul_f32 v[34:35], v[34:35], v[36:37] op_sel:[1,0]
	v_pk_fma_f32 v[62:63], v[66:67], v[38:39], v[70:71]
	v_pk_fma_f32 v[64:65], v[68:69], v[34:35], v[72:73]
	v_pk_fma_f32 v[36:37], v[208:209], v[62:63], v[74:75]
	v_pk_fma_f32 v[34:35], v[206:207], v[64:65], v[76:77]
	v_cvt_pk_bf16_f32 v36, v36, v37
	s_nop 0
	v_cvt_pk_bf16_f32 v34, v34, v35
	s_nop 0
	v_cndmask_b32_e64 v35, v34, v221, s[40:41]
	v_cndmask_b32_e64 v34, v36, v221, s[40:41]
	global_store_dwordx2 v[184:185], v[34:35], off offset:256
	v_or_b32_e32 v34, 0x90, v162
	v_ashrrev_i32_e32 v35, 31, v34
	v_lshlrev_b64 v[38:39], 2, v[34:35]
	v_lshl_add_u64 v[34:35], s[42:43], 0, v[38:39]
	v_lshl_add_u64 v[38:39], s[44:45], 0, v[38:39]
	global_load_dwordx4 v[34:37], v[34:35], off
	s_nop 0
	global_load_dwordx4 v[38:41], v[38:39], off
	s_nop 0
	global_load_dwordx4 v[42:45], v[174:175], off offset:576
	v_mov_b64_e32 v[70:71], v[226:227]
	s_waitcnt lgkmcnt(0)
	v_sub_f32_e32 v5, v5, v70
	v_sub_f32_e32 v4, v4, v70
	v_sub_f32_e32 v3, v3, v70
	v_sub_f32_e32 v2, v2, v70
	v_pk_mul_f32 v[2:3], v[70:71], v[2:3] op_sel:[1,0]
	v_pk_mul_f32 v[4:5], v[70:71], v[4:5] op_sel:[1,0]
	s_waitcnt vmcnt(1)
	v_pk_fma_f32 v[2:3], v[34:35], v[2:3], v[38:39]
	s_waitcnt vmcnt(0)
	v_pk_add_f32 v[66:67], v[44:45], 1.0 op_sel_hi:[1,0]
	v_pk_add_f32 v[68:69], v[42:43], 1.0 op_sel_hi:[1,0]
	global_load_dwordx4 v[42:45], v[172:173], off offset:576
	v_pk_fma_f32 v[4:5], v[36:37], v[4:5], v[40:41]
	s_waitcnt vmcnt(0)
	v_pk_fma_f32 v[72:73], v[68:69], v[2:3], v[42:43]
	v_pk_fma_f32 v[70:71], v[66:67], v[4:5], v[44:45]
	v_cvt_pk_bf16_f32 v72, v72, v73
	s_nop 0
	v_cvt_pk_bf16_f32 v70, v70, v71
	s_nop 0
	v_cndmask_b32_e64 v71, v70, v221, s[40:41]
	v_cndmask_b32_e64 v70, v72, v221, s[40:41]
	global_store_dwordx2 v[178:179], v[70:71], off offset:288
	v_mov_b64_e32 v[70:71], v[228:229]
	s_waitcnt lgkmcnt(0)
	v_sub_f32_e32 v9, v9, v70
	v_sub_f32_e32 v8, v8, v70
	v_sub_f32_e32 v7, v7, v70
	v_sub_f32_e32 v6, v6, v70
	v_pk_mul_f32 v[6:7], v[70:71], v[6:7] op_sel:[1,0]
	v_pk_mul_f32 v[8:9], v[70:71], v[8:9] op_sel:[1,0]
	v_pk_fma_f32 v[6:7], v[34:35], v[6:7], v[38:39]
	v_pk_fma_f32 v[8:9], v[36:37], v[8:9], v[40:41]
	v_pk_fma_f32 v[72:73], v[68:69], v[6:7], v[42:43]
	v_pk_fma_f32 v[70:71], v[66:67], v[8:9], v[44:45]
	v_cvt_pk_bf16_f32 v72, v72, v73
	s_nop 0
	v_cvt_pk_bf16_f32 v70, v70, v71
	s_nop 0
	v_cndmask_b32_e64 v71, v70, v221, s[40:41]
	v_cndmask_b32_e64 v70, v72, v221, s[40:41]
	global_store_dwordx2 v[176:177], v[70:71], off offset:288
	v_mov_b64_e32 v[70:71], v[230:231]
	s_waitcnt lgkmcnt(0)
	v_sub_f32_e32 v13, v13, v70
	v_sub_f32_e32 v12, v12, v70
	v_sub_f32_e32 v11, v11, v70
	v_sub_f32_e32 v10, v10, v70
	v_pk_mul_f32 v[10:11], v[70:71], v[10:11] op_sel:[1,0]
	v_pk_mul_f32 v[12:13], v[70:71], v[12:13] op_sel:[1,0]
	v_pk_fma_f32 v[10:11], v[34:35], v[10:11], v[38:39]
	v_pk_fma_f32 v[12:13], v[36:37], v[12:13], v[40:41]
	v_pk_fma_f32 v[72:73], v[68:69], v[10:11], v[42:43]
	v_pk_fma_f32 v[70:71], v[66:67], v[12:13], v[44:45]
	v_cvt_pk_bf16_f32 v72, v72, v73
	s_nop 0
	v_cvt_pk_bf16_f32 v70, v70, v71
	s_nop 0
	v_cndmask_b32_e64 v71, v70, v221, s[40:41]
	v_cndmask_b32_e64 v70, v72, v221, s[40:41]
	global_store_dwordx2 v[180:181], v[70:71], off offset:288
	v_mov_b64_e32 v[70:71], v[232:233]
	s_waitcnt lgkmcnt(0)
	v_sub_f32_e32 v17, v17, v70
	v_sub_f32_e32 v16, v16, v70
	v_sub_f32_e32 v15, v15, v70
	v_sub_f32_e32 v14, v14, v70
	v_pk_mul_f32 v[14:15], v[70:71], v[14:15] op_sel:[1,0]
	v_pk_mul_f32 v[16:17], v[70:71], v[16:17] op_sel:[1,0]
	v_pk_fma_f32 v[14:15], v[34:35], v[14:15], v[38:39]
	v_pk_fma_f32 v[16:17], v[36:37], v[16:17], v[40:41]
	v_pk_fma_f32 v[72:73], v[68:69], v[14:15], v[42:43]
	v_pk_fma_f32 v[70:71], v[66:67], v[16:17], v[44:45]
	v_cvt_pk_bf16_f32 v72, v72, v73
	s_nop 0
	v_cvt_pk_bf16_f32 v70, v70, v71
	s_nop 0
	v_cndmask_b32_e64 v71, v70, v221, s[40:41]
	v_cndmask_b32_e64 v70, v72, v221, s[40:41]
	global_store_dwordx2 v[182:183], v[70:71], off offset:288
	v_mov_b64_e32 v[70:71], v[234:235]
	s_waitcnt lgkmcnt(0)
	v_sub_f32_e32 v21, v21, v70
	v_sub_f32_e32 v20, v20, v70
	v_sub_f32_e32 v19, v19, v70
	v_sub_f32_e32 v18, v18, v70
	v_pk_mul_f32 v[18:19], v[70:71], v[18:19] op_sel:[1,0]
	v_pk_mul_f32 v[20:21], v[70:71], v[20:21] op_sel:[1,0]
	v_pk_fma_f32 v[18:19], v[34:35], v[18:19], v[38:39]
	v_pk_fma_f32 v[20:21], v[36:37], v[20:21], v[40:41]
	v_pk_fma_f32 v[72:73], v[68:69], v[18:19], v[42:43]
	v_pk_fma_f32 v[70:71], v[66:67], v[20:21], v[44:45]
	v_cvt_pk_bf16_f32 v72, v72, v73
	s_nop 0
	v_cvt_pk_bf16_f32 v70, v70, v71
	s_nop 0
	v_cndmask_b32_e64 v71, v70, v221, s[40:41]
	v_cndmask_b32_e64 v70, v72, v221, s[40:41]
	global_store_dwordx2 v[204:205], v[70:71], off offset:288
	v_mov_b64_e32 v[70:71], v[236:237]
	s_waitcnt lgkmcnt(0)
	v_sub_f32_e32 v25, v25, v70
	v_sub_f32_e32 v24, v24, v70
	v_sub_f32_e32 v23, v23, v70
	v_sub_f32_e32 v22, v22, v70
	v_pk_mul_f32 v[22:23], v[70:71], v[22:23] op_sel:[1,0]
	v_pk_mul_f32 v[24:25], v[70:71], v[24:25] op_sel:[1,0]
	v_pk_fma_f32 v[22:23], v[34:35], v[22:23], v[38:39]
	v_pk_fma_f32 v[24:25], v[36:37], v[24:25], v[40:41]
	v_pk_fma_f32 v[72:73], v[68:69], v[22:23], v[42:43]
	v_pk_fma_f32 v[70:71], v[66:67], v[24:25], v[44:45]
	v_cvt_pk_bf16_f32 v72, v72, v73
	s_nop 0
	v_cvt_pk_bf16_f32 v70, v70, v71
	s_nop 0
	v_cndmask_b32_e64 v71, v70, v221, s[40:41]
	v_cndmask_b32_e64 v70, v72, v221, s[40:41]
	global_store_dwordx2 v[202:203], v[70:71], off offset:288
	v_mov_b64_e32 v[70:71], v[238:239]
	s_waitcnt lgkmcnt(0)
	v_sub_f32_e32 v29, v29, v70
	v_sub_f32_e32 v28, v28, v70
	v_sub_f32_e32 v27, v27, v70
	v_sub_f32_e32 v26, v26, v70
	v_pk_mul_f32 v[26:27], v[70:71], v[26:27] op_sel:[1,0]
	v_pk_mul_f32 v[28:29], v[70:71], v[28:29] op_sel:[1,0]
	v_pk_fma_f32 v[26:27], v[34:35], v[26:27], v[38:39]
	v_pk_fma_f32 v[28:29], v[36:37], v[28:29], v[40:41]
	v_pk_fma_f32 v[72:73], v[68:69], v[26:27], v[42:43]
	v_pk_fma_f32 v[70:71], v[66:67], v[28:29], v[44:45]
	v_cvt_pk_bf16_f32 v72, v72, v73
	s_nop 0
	v_cvt_pk_bf16_f32 v70, v70, v71
	s_nop 0
	v_cndmask_b32_e64 v71, v70, v221, s[40:41]
	v_cndmask_b32_e64 v70, v72, v221, s[40:41]
	global_store_dwordx2 v[200:201], v[70:71], off offset:288
	v_mov_b64_e32 v[70:71], v[240:241]
	s_waitcnt lgkmcnt(0)
	v_sub_f32_e32 v33, v33, v70
	v_sub_f32_e32 v32, v32, v70
	v_sub_f32_e32 v31, v31, v70
	v_sub_f32_e32 v30, v30, v70
	v_pk_mul_f32 v[30:31], v[70:71], v[30:31] op_sel:[1,0]
	v_pk_mul_f32 v[32:33], v[70:71], v[32:33] op_sel:[1,0]
	v_pk_fma_f32 v[30:31], v[34:35], v[30:31], v[38:39]
	v_pk_fma_f32 v[32:33], v[36:37], v[32:33], v[40:41]
	v_pk_fma_f32 v[36:37], v[68:69], v[30:31], v[42:43]
	v_pk_fma_f32 v[34:35], v[66:67], v[32:33], v[44:45]
	v_cvt_pk_bf16_f32 v36, v36, v37
	s_nop 0
	v_cvt_pk_bf16_f32 v34, v34, v35
	s_nop 0
	v_cndmask_b32_e64 v35, v34, v221, s[40:41]
	v_cndmask_b32_e64 v34, v36, v221, s[40:41]
	global_store_dwordx2 v[184:185], v[34:35], off offset:288
	v_mov_b32_e32 v34, v0
	s_cbranch_vccnz .LBB0_3287
	s_add_u32 s0, s6, 0x2100000
	v_lshlrev_b32_e32 v35, 4, v34
	s_addc_u32 s1, s7, 0
	v_readlane_b32 s6, v251, 18
	v_and_b32_e32 v36, 0xfffffc00, v35
	v_ashrrev_i32_e32 v35, 31, v34
	v_readlane_b32 s7, v251, 19
	v_readlane_b32 s8, v251, 25
	s_nop 0
	v_lshl_add_u64 v[34:35], v[34:35], 4, s[6:7]
	s_mov_b64 s[6:7], 0
	v_add_u32_e32 v36, s8, v36
